# plus ssq row-scale loads of the xq and ff1 epilogues hoisted: all 8 per-step loads issued at step 0
# speedup vs baseline: 1.0099x; 1.0005x over previous
; DI u32x4 pk8(const f32x4& a, const f32x4& b) { u32x4 w; w.x = pk2(a[0], a[1]); w.y = pk2(a[2], a[3]); w.z = pk2(b[0], b[1]); w.w = pk2(b[2], b[3]); return w; }
; template <bool NT = false> DI void st_rows16(void* base, unsigned pitch_b, unsigned row0, unsigned col0, int fr, int fq, const u32x4& w0, const u32x4& w1) {
;   u32x4 x;
; #pragma unroll
;   for (int e = 0; e < 4; ++e) x[e] = (unsigned)__builtin_amdgcn_update_dpp(0, (int)w1[e], 0x128  , 0xf, 0xf, false);
;   const bool hi = fr >= 8;
;   u32x4 pa, pb;
; #pragma unroll
;   for (int e = 0; e < 4; ++e) { pa[e] = hi ? x[e] : w0[e]; pb[e] = hi ? w0[e] : x[e]; }
;   const unsigned ra = row0 + (unsigned)(fr & 7), ca = col0 + 8u * fq + (hi ? 32u : 0u), cb = col0 + 8u * fq + (hi ? 0u : 32u);
;   if (NT) { __builtin_nontemporal_store(pa, (u32x4*)((char*)base + (ra * pitch_b + ca * 2u))); __builtin_nontemporal_store(pb, (u32x4*)((char*)base + ((ra + 8u) * pitch_b + cb * 2u))); }
;   else { gst<u32x4>(base, ra * pitch_b + ca * 2u, pa); gst<u32x4>(base, (ra + 8u) * pitch_b + cb * 2u, pb); }
;   DI void operator()(g8::Acc& acc, int pm, int pn, int wr, int wc, int fr, int fq) const {
;     ...
;     for (int ai = 0; ai < 2; ++ai)
; #pragma unroll
;       for (int m = 0; m < 4; ++m) {
;         const int row = pm * BM + ai * HALF + wr * 64 + m * 16 + fr; const float rs = rsqrtf(ssq[row] * (1.0f / DM) + RMS_EPS) * sc;
;         u32x4 wv[2];
; #pragma unroll
;         for (int bj = 0; bj < 2; ++bj) {
;           f32x4 o0 = acc[ai][bj][m][0] * rs, o1 = acc[ai][bj][m][1] * rs;
;           if (act) {
; #pragma unroll
;             for (int e = 0; e < 4; ++e) { const float a = fmaxf(o0[e], 0.f), b = fmaxf(o1[e], 0.f); o0[e] = a * a; o1[e] = b * b; } }
;           wv[bj] = pk8(o0, o1);
;         }
;         st_rows16(dst, (unsigned)ld * 2u, (unsigned)(row - fr), (unsigned)(pn * BM + wc * 64), fr, fq, wv[0], wv[1]);
;         __builtin_amdgcn_sched_barrier(0);
.LBB0_623:
	s_lshl_b32 s1, s46, 8
	s_add_i32 s1, s1, s14
	v_or_b32_e32 v150, s1, v140
	v_ashrrev_i32_e32 v151, 31, v150
	v_lshl_add_u64 v[150:151], v[150:151], 2, s[78:79]
	global_load_dword v232, v[150:151], off
	global_load_dword v233, v[150:151], off offset:64
	global_load_dword v234, v[150:151], off offset:128
	global_load_dword v235, v[150:151], off offset:192
	global_load_dword v236, v[150:151], off offset:512
	global_load_dword v237, v[150:151], off offset:576
	global_load_dword v238, v[150:151], off offset:640
	global_load_dword v239, v[150:151], off offset:704
	v_mov_b32_e32 v153, 0
	v_lshl_or_b32 v150, s0, 8, v145
	v_mov_b32_e32 v154, 0
	v_mov_b32_e32 v155, 0
	v_mov_b32_e32 v156, 0
	v_or_b32_e32 v151, v150, v143
	v_or_b32_e32 v157, s1, v142
	v_or_b32_e32 v150, v150, v144
	v_lshlrev_b32_e32 v151, 1, v151
	v_lshlrev_b32_e32 v157, 11, v157
	v_lshlrev_b32_e32 v150, 1, v150
	s_waitcnt vmcnt(0)
	v_fmamk_f32 v152, v232, 0x3a800000, v149
	v_mul_f32_e32 v158, 0x4b800000, v152
	v_cmp_gt_f32_e32 vcc, s21, v152
	s_nop 1
	v_cndmask_b32_e32 v152, v152, v158, vcc
	v_rsq_f32_e32 v152, v152
	v_add_u32_e32 v158, v151, v157
	v_add3_u32 v157, v150, v157, s11
	v_mul_f32_e32 v159, 0x45800000, v152
	v_cndmask_b32_e32 v152, v152, v159, vcc
	v_mul_f32_e32 v152, 0x3db8aa3b, v152
	v_pk_mul_f32 v[118:119], v[118:119], v[152:153] op_sel_hi:[1,0]
	v_pk_mul_f32 v[116:117], v[116:117], v[152:153] op_sel_hi:[1,0]
	v_pk_mul_f32 v[114:115], v[114:115], v[152:153] op_sel_hi:[1,0]
	v_pk_mul_f32 v[112:113], v[112:113], v[152:153] op_sel_hi:[1,0]
	v_pk_mul_f32 v[126:127], v[126:127], v[152:153] op_sel_hi:[1,0]
	v_pk_mul_f32 v[124:125], v[124:125], v[152:153] op_sel_hi:[1,0]
	v_pk_mul_f32 v[122:123], v[122:123], v[152:153] op_sel_hi:[1,0]
	v_pk_mul_f32 v[120:121], v[120:121], v[152:153] op_sel_hi:[1,0]
	v_cvt_pk_bf16_f32 v116, v116, v117
	v_cvt_pk_bf16_f32 v117, v118, v119
	v_cvt_pk_bf16_f32 v112, v112, v113
	v_cvt_pk_bf16_f32 v113, v114, v115
	v_cvt_pk_bf16_f32 v124, v124, v125
	v_cvt_pk_bf16_f32 v125, v126, v127
	v_cvt_pk_bf16_f32 v120, v120, v121
	v_cvt_pk_bf16_f32 v121, v122, v123
	v_mov_b32_dpp v153, v116 row_ror:8 row_mask:0xf bank_mask:0xf
	v_mov_b32_dpp v154, v117 row_ror:8 row_mask:0xf bank_mask:0xf
	v_mov_b32_dpp v155, v112 row_ror:8 row_mask:0xf bank_mask:0xf
	v_mov_b32_dpp v156, v113 row_ror:8 row_mask:0xf bank_mask:0xf
	v_cndmask_b32_e64 v112, v124, v153, s[4:5]
	v_cndmask_b32_e64 v113, v125, v154, s[4:5]
	v_cndmask_b32_e64 v114, v120, v155, s[4:5]
	v_cndmask_b32_e64 v115, v121, v156, s[4:5]
	v_cndmask_b32_e64 v116, v153, v124, s[4:5]
	v_cndmask_b32_e64 v117, v154, v125, s[4:5]
	v_cndmask_b32_e64 v118, v155, v120, s[4:5]
	v_cndmask_b32_e64 v119, v156, v121, s[4:5]
	global_store_dwordx4 v158, v[112:115], s[26:27]
	global_store_dwordx4 v157, v[116:119], s[26:27]
	s_or_b32 s0, s1, 16
	v_mov_b32_e32 v113, 0
	v_mov_b32_e32 v114, 0
	v_mov_b32_e32 v115, 0
	v_mov_b32_e32 v116, 0
	v_or_b32_e32 v117, s0, v142
	v_lshlrev_b32_e32 v117, 11, v117
	v_fmamk_f32 v112, v233, 0x3a800000, v149
	v_mul_f32_e32 v118, 0x4b800000, v112
	v_cmp_gt_f32_e32 vcc, s21, v112
	s_nop 1
	v_cndmask_b32_e32 v112, v112, v118, vcc
	v_rsq_f32_e32 v112, v112
	v_add_u32_e32 v118, v151, v117
	v_add3_u32 v117, v150, v117, s11
	v_mul_f32_e32 v119, 0x45800000, v112
	v_cndmask_b32_e32 v112, v112, v119, vcc
	v_mul_f32_e32 v112, 0x3db8aa3b, v112
	v_pk_mul_f32 v[102:103], v[102:103], v[112:113] op_sel_hi:[1,0]
	v_pk_mul_f32 v[100:101], v[100:101], v[112:113] op_sel_hi:[1,0]
	v_pk_mul_f32 v[98:99], v[98:99], v[112:113] op_sel_hi:[1,0]
	v_pk_mul_f32 v[96:97], v[96:97], v[112:113] op_sel_hi:[1,0]
	v_pk_mul_f32 v[110:111], v[110:111], v[112:113] op_sel_hi:[1,0]
	v_pk_mul_f32 v[108:109], v[108:109], v[112:113] op_sel_hi:[1,0]
	v_pk_mul_f32 v[106:107], v[106:107], v[112:113] op_sel_hi:[1,0]
	v_pk_mul_f32 v[104:105], v[104:105], v[112:113] op_sel_hi:[1,0]
	v_cvt_pk_bf16_f32 v100, v100, v101
	v_cvt_pk_bf16_f32 v101, v102, v103
	v_cvt_pk_bf16_f32 v96, v96, v97
	v_cvt_pk_bf16_f32 v97, v98, v99
	v_cvt_pk_bf16_f32 v108, v108, v109
	v_cvt_pk_bf16_f32 v109, v110, v111
	v_cvt_pk_bf16_f32 v104, v104, v105
	v_cvt_pk_bf16_f32 v105, v106, v107
	v_mov_b32_dpp v113, v100 row_ror:8 row_mask:0xf bank_mask:0xf
	v_mov_b32_dpp v114, v101 row_ror:8 row_mask:0xf bank_mask:0xf
	v_mov_b32_dpp v115, v96 row_ror:8 row_mask:0xf bank_mask:0xf
	v_mov_b32_dpp v116, v97 row_ror:8 row_mask:0xf bank_mask:0xf
	v_cndmask_b32_e64 v96, v108, v113, s[4:5]
	v_cndmask_b32_e64 v97, v109, v114, s[4:5]
	v_cndmask_b32_e64 v98, v104, v115, s[4:5]
	v_cndmask_b32_e64 v99, v105, v116, s[4:5]
	v_cndmask_b32_e64 v100, v113, v108, s[4:5]
	v_cndmask_b32_e64 v101, v114, v109, s[4:5]
	v_cndmask_b32_e64 v102, v115, v104, s[4:5]
	v_cndmask_b32_e64 v103, v116, v105, s[4:5]
	global_store_dwordx4 v118, v[96:99], s[26:27]
	global_store_dwordx4 v117, v[100:103], s[26:27]
	s_or_b32 s0, s1, 32
	v_mov_b32_e32 v97, 0
	v_mov_b32_e32 v98, 0
	v_mov_b32_e32 v99, 0
	v_mov_b32_e32 v100, 0
	v_or_b32_e32 v101, s0, v142
	v_lshlrev_b32_e32 v101, 11, v101
	v_fmamk_f32 v96, v234, 0x3a800000, v149
	v_mul_f32_e32 v102, 0x4b800000, v96
	v_cmp_gt_f32_e32 vcc, s21, v96
	s_nop 1
	v_cndmask_b32_e32 v96, v96, v102, vcc
	v_rsq_f32_e32 v96, v96
	v_add_u32_e32 v102, v151, v101
	v_add3_u32 v101, v150, v101, s11
	v_mul_f32_e32 v103, 0x45800000, v96
	v_cndmask_b32_e32 v96, v96, v103, vcc
	v_mul_f32_e32 v96, 0x3db8aa3b, v96
	v_pk_mul_f32 v[86:87], v[86:87], v[96:97] op_sel_hi:[1,0]
	v_pk_mul_f32 v[84:85], v[84:85], v[96:97] op_sel_hi:[1,0]
	v_pk_mul_f32 v[82:83], v[82:83], v[96:97] op_sel_hi:[1,0]
	v_pk_mul_f32 v[80:81], v[80:81], v[96:97] op_sel_hi:[1,0]
	v_pk_mul_f32 v[94:95], v[94:95], v[96:97] op_sel_hi:[1,0]
; DI u32x4 pk8(const f32x4& a, const f32x4& b) { u32x4 w; w.x = pk2(a[0], a[1]); w.y = pk2(a[2], a[3]); w.z = pk2(b[0], b[1]); w.w = pk2(b[2], b[3]); return w; }
; template <bool NT = false> DI void st_rows16(void* base, unsigned pitch_b, unsigned row0, unsigned col0, int fr, int fq, const u32x4& w0, const u32x4& w1) {
;   u32x4 x;
; #pragma unroll
;   for (int e = 0; e < 4; ++e) x[e] = (unsigned)__builtin_amdgcn_update_dpp(0, (int)w1[e], 0x128  , 0xf, 0xf, false);
;   const bool hi = fr >= 8;
;   u32x4 pa, pb;
; #pragma unroll
;   for (int e = 0; e < 4; ++e) { pa[e] = hi ? x[e] : w0[e]; pb[e] = hi ? w0[e] : x[e]; }
;   const unsigned ra = row0 + (unsigned)(fr & 7), ca = col0 + 8u * fq + (hi ? 32u : 0u), cb = col0 + 8u * fq + (hi ? 0u : 32u);
;   if (NT) { __builtin_nontemporal_store(pa, (u32x4*)((char*)base + (ra * pitch_b + ca * 2u))); __builtin_nontemporal_store(pb, (u32x4*)((char*)base + ((ra + 8u) * pitch_b + cb * 2u))); }
;   else { gst<u32x4>(base, ra * pitch_b + ca * 2u, pa); gst<u32x4>(base, (ra + 8u) * pitch_b + cb * 2u, pb); }
;   DI void operator()(g8::Acc& acc, int pm, int pn, int wr, int wc, int fr, int fq) const {
;     ...
;     for (int ai = 0; ai < 2; ++ai)
; #pragma unroll
;       for (int m = 0; m < 4; ++m) {
;         const int row = pm * BM + ai * HALF + wr * 64 + m * 16 + fr; const float rs = rsqrtf(ssq[row] * (1.0f / DM) + RMS_EPS) * sc;
;         u32x4 wv[2];
; #pragma unroll
;         for (int bj = 0; bj < 2; ++bj) {
;           f32x4 o0 = acc[ai][bj][m][0] * rs, o1 = acc[ai][bj][m][1] * rs;
;           if (act) {
; #pragma unroll
;             for (int e = 0; e < 4; ++e) { const float a = fmaxf(o0[e], 0.f), b = fmaxf(o1[e], 0.f); o0[e] = a * a; o1[e] = b * b; } }
;           wv[bj] = pk8(o0, o1);
;         }
;         st_rows16(dst, (unsigned)ld * 2u, (unsigned)(row - fr), (unsigned)(pn * BM + wc * 64), fr, fq, wv[0], wv[1]);
;         __builtin_amdgcn_sched_barrier(0);
	v_pk_mul_f32 v[92:93], v[92:93], v[96:97] op_sel_hi:[1,0]
	v_pk_mul_f32 v[90:91], v[90:91], v[96:97] op_sel_hi:[1,0]
	v_pk_mul_f32 v[88:89], v[88:89], v[96:97] op_sel_hi:[1,0]
	v_cvt_pk_bf16_f32 v84, v84, v85
	v_cvt_pk_bf16_f32 v85, v86, v87
	v_cvt_pk_bf16_f32 v80, v80, v81
	v_cvt_pk_bf16_f32 v81, v82, v83
	v_cvt_pk_bf16_f32 v92, v92, v93
	v_cvt_pk_bf16_f32 v93, v94, v95
	v_cvt_pk_bf16_f32 v88, v88, v89
	v_cvt_pk_bf16_f32 v89, v90, v91
	v_mov_b32_dpp v97, v84 row_ror:8 row_mask:0xf bank_mask:0xf
	v_mov_b32_dpp v98, v85 row_ror:8 row_mask:0xf bank_mask:0xf
	v_mov_b32_dpp v99, v80 row_ror:8 row_mask:0xf bank_mask:0xf
	v_mov_b32_dpp v100, v81 row_ror:8 row_mask:0xf bank_mask:0xf
	v_cndmask_b32_e64 v80, v92, v97, s[4:5]
	v_cndmask_b32_e64 v81, v93, v98, s[4:5]
	v_cndmask_b32_e64 v82, v88, v99, s[4:5]
	v_cndmask_b32_e64 v83, v89, v100, s[4:5]
	v_cndmask_b32_e64 v84, v97, v92, s[4:5]
	v_cndmask_b32_e64 v85, v98, v93, s[4:5]
	v_cndmask_b32_e64 v86, v99, v88, s[4:5]
	v_cndmask_b32_e64 v87, v100, v89, s[4:5]
	global_store_dwordx4 v102, v[80:83], s[26:27]
	global_store_dwordx4 v101, v[84:87], s[26:27]
	s_or_b32 s0, s1, 48
	v_mov_b32_e32 v81, 0
	v_mov_b32_e32 v82, 0
	v_mov_b32_e32 v83, 0
	v_mov_b32_e32 v84, 0
	v_or_b32_e32 v85, s0, v142
	v_lshlrev_b32_e32 v85, 11, v85
	v_fmamk_f32 v80, v235, 0x3a800000, v149
	v_mul_f32_e32 v86, 0x4b800000, v80
	v_cmp_gt_f32_e32 vcc, s21, v80
	s_nop 1
	v_cndmask_b32_e32 v80, v80, v86, vcc
	v_rsq_f32_e32 v80, v80
	v_add_u32_e32 v86, v151, v85
	v_add3_u32 v85, v150, v85, s11
	v_mul_f32_e32 v87, 0x45800000, v80
	v_cndmask_b32_e32 v80, v80, v87, vcc
	v_mul_f32_e32 v80, 0x3db8aa3b, v80
	v_pk_mul_f32 v[70:71], v[70:71], v[80:81] op_sel_hi:[1,0]
	v_pk_mul_f32 v[68:69], v[68:69], v[80:81] op_sel_hi:[1,0]
	v_pk_mul_f32 v[66:67], v[66:67], v[80:81] op_sel_hi:[1,0]
	v_pk_mul_f32 v[64:65], v[64:65], v[80:81] op_sel_hi:[1,0]
	v_pk_mul_f32 v[78:79], v[78:79], v[80:81] op_sel_hi:[1,0]
	v_pk_mul_f32 v[76:77], v[76:77], v[80:81] op_sel_hi:[1,0]
	v_pk_mul_f32 v[74:75], v[74:75], v[80:81] op_sel_hi:[1,0]
	v_pk_mul_f32 v[72:73], v[72:73], v[80:81] op_sel_hi:[1,0]
	v_cvt_pk_bf16_f32 v68, v68, v69
	v_cvt_pk_bf16_f32 v69, v70, v71
	v_cvt_pk_bf16_f32 v64, v64, v65
	v_cvt_pk_bf16_f32 v65, v66, v67
	v_cvt_pk_bf16_f32 v76, v76, v77
	v_cvt_pk_bf16_f32 v77, v78, v79
	v_cvt_pk_bf16_f32 v72, v72, v73
	v_cvt_pk_bf16_f32 v73, v74, v75
	v_mov_b32_dpp v81, v68 row_ror:8 row_mask:0xf bank_mask:0xf
	v_mov_b32_dpp v82, v69 row_ror:8 row_mask:0xf bank_mask:0xf
	v_mov_b32_dpp v83, v64 row_ror:8 row_mask:0xf bank_mask:0xf
	v_mov_b32_dpp v84, v65 row_ror:8 row_mask:0xf bank_mask:0xf
	v_cndmask_b32_e64 v64, v76, v81, s[4:5]
	v_cndmask_b32_e64 v65, v77, v82, s[4:5]
	v_cndmask_b32_e64 v66, v72, v83, s[4:5]
	v_cndmask_b32_e64 v67, v73, v84, s[4:5]
	v_cndmask_b32_e64 v68, v81, v76, s[4:5]
	v_cndmask_b32_e64 v69, v82, v77, s[4:5]
	v_cndmask_b32_e64 v70, v83, v72, s[4:5]
	v_cndmask_b32_e64 v71, v84, v73, s[4:5]
	global_store_dwordx4 v86, v[64:67], s[26:27]
	global_store_dwordx4 v85, v[68:71], s[26:27]
	s_add_i32 s0, s1, 0x80
	v_mov_b32_e32 v65, 0
	v_mov_b32_e32 v66, 0
	v_mov_b32_e32 v67, 0
	v_mov_b32_e32 v68, 0
	v_or_b32_e32 v69, s0, v142
	v_lshlrev_b32_e32 v69, 11, v69
	v_fmamk_f32 v64, v236, 0x3a800000, v149
	v_mul_f32_e32 v70, 0x4b800000, v64
	v_cmp_gt_f32_e32 vcc, s21, v64
	s_nop 1
	v_cndmask_b32_e32 v64, v64, v70, vcc
	v_rsq_f32_e32 v64, v64
	v_add_u32_e32 v70, v151, v69
	v_add3_u32 v69, v150, v69, s11
	v_mul_f32_e32 v71, 0x45800000, v64
	v_cndmask_b32_e32 v64, v64, v71, vcc
	v_mul_f32_e32 v64, 0x3db8aa3b, v64
	v_pk_mul_f32 v[54:55], v[54:55], v[64:65] op_sel_hi:[1,0]
	v_pk_mul_f32 v[52:53], v[52:53], v[64:65] op_sel_hi:[1,0]
	v_pk_mul_f32 v[50:51], v[50:51], v[64:65] op_sel_hi:[1,0]
	v_pk_mul_f32 v[48:49], v[48:49], v[64:65] op_sel_hi:[1,0]
	v_pk_mul_f32 v[62:63], v[62:63], v[64:65] op_sel_hi:[1,0]
	v_pk_mul_f32 v[60:61], v[60:61], v[64:65] op_sel_hi:[1,0]
	v_pk_mul_f32 v[58:59], v[58:59], v[64:65] op_sel_hi:[1,0]
	v_pk_mul_f32 v[56:57], v[56:57], v[64:65] op_sel_hi:[1,0]
	v_cvt_pk_bf16_f32 v52, v52, v53
	v_cvt_pk_bf16_f32 v53, v54, v55
	v_cvt_pk_bf16_f32 v48, v48, v49
	v_cvt_pk_bf16_f32 v49, v50, v51
	v_cvt_pk_bf16_f32 v60, v60, v61
	v_cvt_pk_bf16_f32 v61, v62, v63
	v_cvt_pk_bf16_f32 v56, v56, v57
	v_cvt_pk_bf16_f32 v57, v58, v59
	v_mov_b32_dpp v65, v52 row_ror:8 row_mask:0xf bank_mask:0xf
	v_mov_b32_dpp v66, v53 row_ror:8 row_mask:0xf bank_mask:0xf
	v_mov_b32_dpp v67, v48 row_ror:8 row_mask:0xf bank_mask:0xf
	v_mov_b32_dpp v68, v49 row_ror:8 row_mask:0xf bank_mask:0xf
	v_cndmask_b32_e64 v48, v60, v65, s[4:5]
	v_cndmask_b32_e64 v49, v61, v66, s[4:5]
	v_cndmask_b32_e64 v50, v56, v67, s[4:5]
	v_cndmask_b32_e64 v51, v57, v68, s[4:5]
	v_cndmask_b32_e64 v52, v65, v60, s[4:5]
	v_cndmask_b32_e64 v53, v66, v61, s[4:5]
	v_cndmask_b32_e64 v54, v67, v56, s[4:5]
	v_cndmask_b32_e64 v55, v68, v57, s[4:5]
	global_store_dwordx4 v70, v[48:51], s[26:27]
	global_store_dwordx4 v69, v[52:55], s[26:27]
	s_add_i32 s0, s1, 0x90
	v_mov_b32_e32 v49, 0
	v_mov_b32_e32 v50, 0
	v_mov_b32_e32 v51, 0
	v_mov_b32_e32 v52, 0
	v_or_b32_e32 v53, s0, v142
	v_lshlrev_b32_e32 v53, 11, v53
	v_fmamk_f32 v48, v237, 0x3a800000, v149
	v_mul_f32_e32 v54, 0x4b800000, v48
	v_cmp_gt_f32_e32 vcc, s21, v48
	s_nop 1
	v_cndmask_b32_e32 v48, v48, v54, vcc
	v_rsq_f32_e32 v48, v48
	v_add_u32_e32 v54, v151, v53
	v_add3_u32 v53, v150, v53, s11
	v_mul_f32_e32 v55, 0x45800000, v48
; DI u32x4 pk8(const f32x4& a, const f32x4& b) { u32x4 w; w.x = pk2(a[0], a[1]); w.y = pk2(a[2], a[3]); w.z = pk2(b[0], b[1]); w.w = pk2(b[2], b[3]); return w; }
; template <bool NT = false> DI void st_rows16(void* base, unsigned pitch_b, unsigned row0, unsigned col0, int fr, int fq, const u32x4& w0, const u32x4& w1) {
;   u32x4 x;
; #pragma unroll
;   for (int e = 0; e < 4; ++e) x[e] = (unsigned)__builtin_amdgcn_update_dpp(0, (int)w1[e], 0x128  , 0xf, 0xf, false);
;   const bool hi = fr >= 8;
;   u32x4 pa, pb;
; #pragma unroll
;   for (int e = 0; e < 4; ++e) { pa[e] = hi ? x[e] : w0[e]; pb[e] = hi ? w0[e] : x[e]; }
;   const unsigned ra = row0 + (unsigned)(fr & 7), ca = col0 + 8u * fq + (hi ? 32u : 0u), cb = col0 + 8u * fq + (hi ? 0u : 32u);
;   if (NT) { __builtin_nontemporal_store(pa, (u32x4*)((char*)base + (ra * pitch_b + ca * 2u))); __builtin_nontemporal_store(pb, (u32x4*)((char*)base + ((ra + 8u) * pitch_b + cb * 2u))); }
;   else { gst<u32x4>(base, ra * pitch_b + ca * 2u, pa); gst<u32x4>(base, (ra + 8u) * pitch_b + cb * 2u, pb); }
;   DI void operator()(g8::Acc& acc, int pm, int pn, int wr, int wc, int fr, int fq) const {
;     ...
;     for (int ai = 0; ai < 2; ++ai)
; #pragma unroll
;       for (int m = 0; m < 4; ++m) {
;         const int row = pm * BM + ai * HALF + wr * 64 + m * 16 + fr; const float rs = rsqrtf(ssq[row] * (1.0f / DM) + RMS_EPS) * sc;
;         u32x4 wv[2];
; #pragma unroll
;         for (int bj = 0; bj < 2; ++bj) {
;           f32x4 o0 = acc[ai][bj][m][0] * rs, o1 = acc[ai][bj][m][1] * rs;
;           if (act) {
; #pragma unroll
;             for (int e = 0; e < 4; ++e) { const float a = fmaxf(o0[e], 0.f), b = fmaxf(o1[e], 0.f); o0[e] = a * a; o1[e] = b * b; } }
;           wv[bj] = pk8(o0, o1);
;         }
;         st_rows16(dst, (unsigned)ld * 2u, (unsigned)(row - fr), (unsigned)(pn * BM + wc * 64), fr, fq, wv[0], wv[1]);
;         __builtin_amdgcn_sched_barrier(0);
	v_cndmask_b32_e32 v48, v48, v55, vcc
	v_mul_f32_e32 v48, 0x3db8aa3b, v48
	v_pk_mul_f32 v[38:39], v[38:39], v[48:49] op_sel_hi:[1,0]
	v_pk_mul_f32 v[36:37], v[36:37], v[48:49] op_sel_hi:[1,0]
	v_pk_mul_f32 v[34:35], v[34:35], v[48:49] op_sel_hi:[1,0]
	v_pk_mul_f32 v[32:33], v[32:33], v[48:49] op_sel_hi:[1,0]
	v_pk_mul_f32 v[46:47], v[46:47], v[48:49] op_sel_hi:[1,0]
	v_pk_mul_f32 v[44:45], v[44:45], v[48:49] op_sel_hi:[1,0]
	v_pk_mul_f32 v[42:43], v[42:43], v[48:49] op_sel_hi:[1,0]
	v_pk_mul_f32 v[40:41], v[40:41], v[48:49] op_sel_hi:[1,0]
	v_cvt_pk_bf16_f32 v36, v36, v37
	v_cvt_pk_bf16_f32 v37, v38, v39
	v_cvt_pk_bf16_f32 v32, v32, v33
	v_cvt_pk_bf16_f32 v33, v34, v35
	v_cvt_pk_bf16_f32 v44, v44, v45
	v_cvt_pk_bf16_f32 v45, v46, v47
	v_cvt_pk_bf16_f32 v40, v40, v41
	v_cvt_pk_bf16_f32 v41, v42, v43
	v_mov_b32_dpp v49, v36 row_ror:8 row_mask:0xf bank_mask:0xf
	v_mov_b32_dpp v50, v37 row_ror:8 row_mask:0xf bank_mask:0xf
	v_mov_b32_dpp v51, v32 row_ror:8 row_mask:0xf bank_mask:0xf
	v_mov_b32_dpp v52, v33 row_ror:8 row_mask:0xf bank_mask:0xf
	v_cndmask_b32_e64 v32, v44, v49, s[4:5]
	v_cndmask_b32_e64 v33, v45, v50, s[4:5]
	v_cndmask_b32_e64 v34, v40, v51, s[4:5]
	v_cndmask_b32_e64 v35, v41, v52, s[4:5]
	v_cndmask_b32_e64 v36, v49, v44, s[4:5]
	v_cndmask_b32_e64 v37, v50, v45, s[4:5]
	v_cndmask_b32_e64 v38, v51, v40, s[4:5]
	v_cndmask_b32_e64 v39, v52, v41, s[4:5]
	global_store_dwordx4 v54, v[32:35], s[26:27]
	global_store_dwordx4 v53, v[36:39], s[26:27]
	s_add_i32 s0, s1, 0xa0
	v_mov_b32_e32 v33, 0
	v_mov_b32_e32 v34, 0
	v_mov_b32_e32 v35, 0
	v_mov_b32_e32 v36, 0
	v_or_b32_e32 v37, s0, v142
	v_lshlrev_b32_e32 v37, 11, v37
	v_fmamk_f32 v32, v238, 0x3a800000, v149
	v_mul_f32_e32 v38, 0x4b800000, v32
	v_cmp_gt_f32_e32 vcc, s21, v32
	s_nop 1
	v_cndmask_b32_e32 v32, v32, v38, vcc
	v_rsq_f32_e32 v32, v32
	v_add_u32_e32 v38, v151, v37
	v_add3_u32 v37, v150, v37, s11
	v_mul_f32_e32 v39, 0x45800000, v32
	v_cndmask_b32_e32 v32, v32, v39, vcc
	v_mul_f32_e32 v32, 0x3db8aa3b, v32
	v_pk_mul_f32 v[22:23], v[22:23], v[32:33] op_sel_hi:[1,0]
	v_pk_mul_f32 v[20:21], v[20:21], v[32:33] op_sel_hi:[1,0]
	v_pk_mul_f32 v[18:19], v[18:19], v[32:33] op_sel_hi:[1,0]
	v_pk_mul_f32 v[16:17], v[16:17], v[32:33] op_sel_hi:[1,0]
	v_pk_mul_f32 v[30:31], v[30:31], v[32:33] op_sel_hi:[1,0]
	v_pk_mul_f32 v[28:29], v[28:29], v[32:33] op_sel_hi:[1,0]
	v_pk_mul_f32 v[26:27], v[26:27], v[32:33] op_sel_hi:[1,0]
	v_pk_mul_f32 v[24:25], v[24:25], v[32:33] op_sel_hi:[1,0]
	v_cvt_pk_bf16_f32 v20, v20, v21
	v_cvt_pk_bf16_f32 v21, v22, v23
	v_cvt_pk_bf16_f32 v16, v16, v17
	v_cvt_pk_bf16_f32 v17, v18, v19
	v_cvt_pk_bf16_f32 v28, v28, v29
	v_cvt_pk_bf16_f32 v29, v30, v31
	v_cvt_pk_bf16_f32 v24, v24, v25
	v_cvt_pk_bf16_f32 v25, v26, v27
	v_mov_b32_dpp v33, v20 row_ror:8 row_mask:0xf bank_mask:0xf
	v_mov_b32_dpp v34, v21 row_ror:8 row_mask:0xf bank_mask:0xf
	v_mov_b32_dpp v35, v16 row_ror:8 row_mask:0xf bank_mask:0xf
	v_mov_b32_dpp v36, v17 row_ror:8 row_mask:0xf bank_mask:0xf
	v_cndmask_b32_e64 v16, v28, v33, s[4:5]
	v_cndmask_b32_e64 v17, v29, v34, s[4:5]
	v_cndmask_b32_e64 v18, v24, v35, s[4:5]
	v_cndmask_b32_e64 v19, v25, v36, s[4:5]
	v_cndmask_b32_e64 v20, v33, v28, s[4:5]
	v_cndmask_b32_e64 v21, v34, v29, s[4:5]
	v_cndmask_b32_e64 v22, v35, v24, s[4:5]
	v_cndmask_b32_e64 v23, v36, v25, s[4:5]
	global_store_dwordx4 v38, v[16:19], s[26:27]
	global_store_dwordx4 v37, v[20:23], s[26:27]
	s_addk_i32 s1, 0xb0
	v_mov_b32_e32 v17, 0
	v_mov_b32_e32 v18, 0
	v_mov_b32_e32 v19, 0
	v_mov_b32_e32 v20, 0
	v_or_b32_e32 v21, s1, v142
	v_lshlrev_b32_e32 v21, 11, v21
	v_fmamk_f32 v16, v239, 0x3a800000, v149
	v_mul_f32_e32 v22, 0x4b800000, v16
	v_cmp_gt_f32_e32 vcc, s21, v16
	s_nop 1
	v_cndmask_b32_e32 v16, v16, v22, vcc
	v_rsq_f32_e32 v16, v16
	v_add_u32_e32 v22, v151, v21
	v_add3_u32 v21, v150, v21, s11
	v_mul_f32_e32 v23, 0x45800000, v16
	v_cndmask_b32_e32 v16, v16, v23, vcc
	v_mul_f32_e32 v16, 0x3db8aa3b, v16
	v_pk_mul_f32 v[6:7], v[6:7], v[16:17] op_sel_hi:[1,0]
	v_pk_mul_f32 v[4:5], v[4:5], v[16:17] op_sel_hi:[1,0]
	v_pk_mul_f32 v[2:3], v[2:3], v[16:17] op_sel_hi:[1,0]
	v_pk_mul_f32 v[0:1], v[0:1], v[16:17] op_sel_hi:[1,0]
	v_pk_mul_f32 v[12:13], v[12:13], v[16:17] op_sel_hi:[1,0]
	v_pk_mul_f32 v[14:15], v[14:15], v[16:17] op_sel_hi:[1,0]
	v_pk_mul_f32 v[8:9], v[8:9], v[16:17] op_sel_hi:[1,0]
	v_pk_mul_f32 v[10:11], v[10:11], v[16:17] op_sel_hi:[1,0]
	v_cvt_pk_bf16_f32 v4, v4, v5
	v_cvt_pk_bf16_f32 v5, v6, v7
	v_cvt_pk_bf16_f32 v0, v0, v1
	v_cvt_pk_bf16_f32 v1, v2, v3
	v_cvt_pk_bf16_f32 v10, v10, v11
	v_cvt_pk_bf16_f32 v8, v8, v9
	v_cvt_pk_bf16_f32 v9, v14, v15
	v_cvt_pk_bf16_f32 v11, v12, v13
	v_mov_b32_dpp v17, v4 row_ror:8 row_mask:0xf bank_mask:0xf
	v_mov_b32_dpp v18, v5 row_ror:8 row_mask:0xf bank_mask:0xf
	v_mov_b32_dpp v19, v0 row_ror:8 row_mask:0xf bank_mask:0xf
	v_mov_b32_dpp v20, v1 row_ror:8 row_mask:0xf bank_mask:0xf
	v_cndmask_b32_e64 v0, v11, v17, s[4:5]
	v_cndmask_b32_e64 v1, v9, v18, s[4:5]
	v_cndmask_b32_e64 v2, v8, v19, s[4:5]
	v_cndmask_b32_e64 v3, v10, v20, s[4:5]
	v_cndmask_b32_e64 v4, v17, v11, s[4:5]
	v_cndmask_b32_e64 v5, v18, v9, s[4:5]
	v_cndmask_b32_e64 v6, v19, v8, s[4:5]
	v_cndmask_b32_e64 v7, v20, v10, s[4:5]
	global_store_dwordx4 v22, v[0:3], s[26:27]
	global_store_dwordx4 v21, v[4:7], s[26:27]
	s_andn2_b64 vcc, exec, s[38:39]
	s_mov_b64 s[0:1], -1
	s_cbranch_vccnz .LBB0_616
	s_andn2_b64 vcc, exec, s[6:7]
	s_cbranch_vccnz .LBB0_615
	s_barrier
	s_branch .LBB0_615

; DI u32x4 pk8(const f32x4& a, const f32x4& b) { u32x4 w; w.x = pk2(a[0], a[1]); w.y = pk2(a[2], a[3]); w.z = pk2(b[0], b[1]); w.w = pk2(b[2], b[3]); return w; }
; template <bool NT = false> DI void st_rows16(void* base, unsigned pitch_b, unsigned row0, unsigned col0, int fr, int fq, const u32x4& w0, const u32x4& w1) {
;   u32x4 x;
; #pragma unroll
;   for (int e = 0; e < 4; ++e) x[e] = (unsigned)__builtin_amdgcn_update_dpp(0, (int)w1[e], 0x128  , 0xf, 0xf, false);
;   const bool hi = fr >= 8;
;   u32x4 pa, pb;
; #pragma unroll
;   for (int e = 0; e < 4; ++e) { pa[e] = hi ? x[e] : w0[e]; pb[e] = hi ? w0[e] : x[e]; }
;   const unsigned ra = row0 + (unsigned)(fr & 7), ca = col0 + 8u * fq + (hi ? 32u : 0u), cb = col0 + 8u * fq + (hi ? 0u : 32u);
;   if (NT) { __builtin_nontemporal_store(pa, (u32x4*)((char*)base + (ra * pitch_b + ca * 2u))); __builtin_nontemporal_store(pb, (u32x4*)((char*)base + ((ra + 8u) * pitch_b + cb * 2u))); }
;   else { gst<u32x4>(base, ra * pitch_b + ca * 2u, pa); gst<u32x4>(base, (ra + 8u) * pitch_b + cb * 2u, pb); }
;   DI void operator()(g8::Acc& acc, int pm, int pn, int wr, int wc, int fr, int fq) const {
;     ...
;     for (int ai = 0; ai < 2; ++ai)
; #pragma unroll
;       for (int m = 0; m < 4; ++m) {
;         const int row = pm * BM + ai * HALF + wr * 64 + m * 16 + fr; const float rs = rsqrtf(ssq[row] * (1.0f / DM) + RMS_EPS) * sc;
;         u32x4 wv[2];
; #pragma unroll
;         for (int bj = 0; bj < 2; ++bj) {
;           f32x4 o0 = acc[ai][bj][m][0] * rs, o1 = acc[ai][bj][m][1] * rs;
;           if (act) {
; #pragma unroll
;             for (int e = 0; e < 4; ++e) { const float a = fmaxf(o0[e], 0.f), b = fmaxf(o1[e], 0.f); o0[e] = a * a; o1[e] = b * b; } }
;           wv[bj] = pk8(o0, o1);
;         }
;         st_rows16(dst, (unsigned)ld * 2u, (unsigned)(row - fr), (unsigned)(pn * BM + wc * 64), fr, fq, wv[0], wv[1]);
;         __builtin_amdgcn_sched_barrier(0);
.LBB0_763:
	s_lshl_b32 s0, s42, 8
	s_add_i32 s0, s0, s14
	v_or_b32_e32 v150, s0, v140
	v_ashrrev_i32_e32 v151, 31, v150
	v_lshl_add_u64 v[150:151], v[150:151], 2, s[16:17]
	global_load_dword v232, v[150:151], off
	global_load_dword v233, v[150:151], off offset:64
	global_load_dword v234, v[150:151], off offset:128
	global_load_dword v235, v[150:151], off offset:192
	global_load_dword v236, v[150:151], off offset:512
	global_load_dword v237, v[150:151], off offset:576
	global_load_dword v238, v[150:151], off offset:640
	global_load_dword v239, v[150:151], off offset:704
	v_mov_b32_e32 v153, 0
	v_lshl_or_b32 v150, s1, 8, v145
	v_mov_b32_e32 v154, 0
	v_mov_b32_e32 v155, 0
	v_mov_b32_e32 v156, 0
	v_or_b32_e32 v151, v150, v143
	v_or_b32_e32 v157, s0, v142
	v_or_b32_e32 v150, v150, v144
	v_lshlrev_b32_e32 v151, 1, v151
	v_lshlrev_b32_e32 v157, 13, v157
	v_lshlrev_b32_e32 v150, 1, v150
	s_waitcnt vmcnt(0)
	v_fmamk_f32 v152, v232, 0x3a800000, v149
	v_mul_f32_e32 v158, 0x4b800000, v152
	v_cmp_gt_f32_e32 vcc, s21, v152
	s_nop 1
	v_cndmask_b32_e32 v152, v152, v158, vcc
	v_rsq_f32_e32 v152, v152
	v_add_u32_e32 v158, v151, v157
	v_add3_u32 v157, v150, v157, s11
	v_mul_f32_e32 v159, 0x45800000, v152
	v_cndmask_b32_e32 v152, v152, v159, vcc
	v_pk_mul_f32 v[118:119], v[118:119], v[152:153] op_sel_hi:[1,0]
	v_pk_mul_f32 v[116:117], v[116:117], v[152:153] op_sel_hi:[1,0]
	v_pk_mul_f32 v[114:115], v[114:115], v[152:153] op_sel_hi:[1,0]
	v_pk_mul_f32 v[112:113], v[112:113], v[152:153] op_sel_hi:[1,0]
	v_pk_mul_f32 v[126:127], v[126:127], v[152:153] op_sel_hi:[1,0]
	v_pk_mul_f32 v[124:125], v[124:125], v[152:153] op_sel_hi:[1,0]
	v_pk_mul_f32 v[122:123], v[122:123], v[152:153] op_sel_hi:[1,0]
	v_pk_mul_f32 v[120:121], v[120:121], v[152:153] op_sel_hi:[1,0]
	v_max_f32_e32 v116, 0, v116
	v_max_f32_e32 v112, 0, v112
	v_max_f32_e32 v117, 0, v117
	v_max_f32_e32 v113, 0, v113
	v_max_f32_e32 v118, 0, v118
	v_max_f32_e32 v114, 0, v114
	v_max_f32_e32 v119, 0, v119
	v_max_f32_e32 v115, 0, v115
	v_max_f32_e32 v124, 0, v124
	v_max_f32_e32 v120, 0, v120
	v_max_f32_e32 v125, 0, v125
	v_max_f32_e32 v121, 0, v121
	v_max_f32_e32 v126, 0, v126
	v_max_f32_e32 v122, 0, v122
	v_max_f32_e32 v127, 0, v127
	v_max_f32_e32 v123, 0, v123
	v_pk_mul_f32 v[116:117], v[116:117], v[116:117]
	v_pk_mul_f32 v[112:113], v[112:113], v[112:113]
	v_pk_mul_f32 v[118:119], v[118:119], v[118:119]
	v_pk_mul_f32 v[114:115], v[114:115], v[114:115]
	v_pk_mul_f32 v[124:125], v[124:125], v[124:125]
	v_pk_mul_f32 v[120:121], v[120:121], v[120:121]
	v_pk_mul_f32 v[126:127], v[126:127], v[126:127]
	v_pk_mul_f32 v[122:123], v[122:123], v[122:123]
	v_cvt_pk_bf16_f32 v116, v116, v117
	v_cvt_pk_bf16_f32 v117, v118, v119
	v_cvt_pk_bf16_f32 v112, v112, v113
	v_cvt_pk_bf16_f32 v113, v114, v115
	v_cvt_pk_bf16_f32 v124, v124, v125
	v_cvt_pk_bf16_f32 v125, v126, v127
	v_cvt_pk_bf16_f32 v120, v120, v121
	v_cvt_pk_bf16_f32 v121, v122, v123
	v_mov_b32_dpp v153, v116 row_ror:8 row_mask:0xf bank_mask:0xf
	v_mov_b32_dpp v154, v117 row_ror:8 row_mask:0xf bank_mask:0xf
	v_mov_b32_dpp v155, v112 row_ror:8 row_mask:0xf bank_mask:0xf
	v_mov_b32_dpp v156, v113 row_ror:8 row_mask:0xf bank_mask:0xf
	v_cndmask_b32_e64 v112, v124, v153, s[4:5]
	v_cndmask_b32_e64 v113, v125, v154, s[4:5]
	v_cndmask_b32_e64 v114, v120, v155, s[4:5]
	v_cndmask_b32_e64 v115, v121, v156, s[4:5]
	v_cndmask_b32_e64 v116, v153, v124, s[4:5]
	v_cndmask_b32_e64 v117, v154, v125, s[4:5]
	v_cndmask_b32_e64 v118, v155, v120, s[4:5]
	v_cndmask_b32_e64 v119, v156, v121, s[4:5]
	global_store_dwordx4 v158, v[112:115], s[24:25] nt
	global_store_dwordx4 v157, v[116:119], s[24:25] nt
	s_or_b32 s1, s0, 16
	v_mov_b32_e32 v113, 0
	v_mov_b32_e32 v114, 0
	v_mov_b32_e32 v115, 0
	v_mov_b32_e32 v116, 0
	v_or_b32_e32 v117, s1, v142
	v_lshlrev_b32_e32 v117, 13, v117
	v_fmamk_f32 v112, v233, 0x3a800000, v149
	v_mul_f32_e32 v118, 0x4b800000, v112
	v_cmp_gt_f32_e32 vcc, s21, v112
	s_nop 1
	v_cndmask_b32_e32 v112, v112, v118, vcc
	v_rsq_f32_e32 v112, v112
	v_add_u32_e32 v118, v151, v117
	v_add3_u32 v117, v150, v117, s11
	v_mul_f32_e32 v119, 0x45800000, v112
	v_cndmask_b32_e32 v112, v112, v119, vcc
	v_pk_mul_f32 v[102:103], v[102:103], v[112:113] op_sel_hi:[1,0]
	v_pk_mul_f32 v[100:101], v[100:101], v[112:113] op_sel_hi:[1,0]
	v_pk_mul_f32 v[98:99], v[98:99], v[112:113] op_sel_hi:[1,0]
	v_pk_mul_f32 v[96:97], v[96:97], v[112:113] op_sel_hi:[1,0]
	v_pk_mul_f32 v[110:111], v[110:111], v[112:113] op_sel_hi:[1,0]
	v_pk_mul_f32 v[108:109], v[108:109], v[112:113] op_sel_hi:[1,0]
	v_pk_mul_f32 v[106:107], v[106:107], v[112:113] op_sel_hi:[1,0]
	v_pk_mul_f32 v[104:105], v[104:105], v[112:113] op_sel_hi:[1,0]
	v_max_f32_e32 v100, 0, v100
	v_max_f32_e32 v96, 0, v96
	v_max_f32_e32 v101, 0, v101
	v_max_f32_e32 v97, 0, v97
	v_max_f32_e32 v102, 0, v102
	v_max_f32_e32 v98, 0, v98
	v_max_f32_e32 v103, 0, v103
	v_max_f32_e32 v99, 0, v99
	v_max_f32_e32 v108, 0, v108
	v_max_f32_e32 v104, 0, v104
	v_max_f32_e32 v109, 0, v109
	v_max_f32_e32 v105, 0, v105
	v_max_f32_e32 v110, 0, v110
	v_max_f32_e32 v106, 0, v106
	v_max_f32_e32 v111, 0, v111
	v_max_f32_e32 v107, 0, v107
	v_pk_mul_f32 v[100:101], v[100:101], v[100:101]
	v_pk_mul_f32 v[96:97], v[96:97], v[96:97]
	v_pk_mul_f32 v[102:103], v[102:103], v[102:103]
	v_pk_mul_f32 v[98:99], v[98:99], v[98:99]
	v_pk_mul_f32 v[108:109], v[108:109], v[108:109]
	v_pk_mul_f32 v[104:105], v[104:105], v[104:105]
	v_pk_mul_f32 v[110:111], v[110:111], v[110:111]
	v_pk_mul_f32 v[106:107], v[106:107], v[106:107]
	v_cvt_pk_bf16_f32 v100, v100, v101
	v_cvt_pk_bf16_f32 v101, v102, v103
	v_cvt_pk_bf16_f32 v96, v96, v97
	v_cvt_pk_bf16_f32 v97, v98, v99
	v_cvt_pk_bf16_f32 v108, v108, v109
; DI u32x4 pk8(const f32x4& a, const f32x4& b) { u32x4 w; w.x = pk2(a[0], a[1]); w.y = pk2(a[2], a[3]); w.z = pk2(b[0], b[1]); w.w = pk2(b[2], b[3]); return w; }
; template <bool NT = false> DI void st_rows16(void* base, unsigned pitch_b, unsigned row0, unsigned col0, int fr, int fq, const u32x4& w0, const u32x4& w1) {
;   u32x4 x;
; #pragma unroll
;   for (int e = 0; e < 4; ++e) x[e] = (unsigned)__builtin_amdgcn_update_dpp(0, (int)w1[e], 0x128  , 0xf, 0xf, false);
;   const bool hi = fr >= 8;
;   u32x4 pa, pb;
; #pragma unroll
;   for (int e = 0; e < 4; ++e) { pa[e] = hi ? x[e] : w0[e]; pb[e] = hi ? w0[e] : x[e]; }
;   const unsigned ra = row0 + (unsigned)(fr & 7), ca = col0 + 8u * fq + (hi ? 32u : 0u), cb = col0 + 8u * fq + (hi ? 0u : 32u);
;   if (NT) { __builtin_nontemporal_store(pa, (u32x4*)((char*)base + (ra * pitch_b + ca * 2u))); __builtin_nontemporal_store(pb, (u32x4*)((char*)base + ((ra + 8u) * pitch_b + cb * 2u))); }
;   else { gst<u32x4>(base, ra * pitch_b + ca * 2u, pa); gst<u32x4>(base, (ra + 8u) * pitch_b + cb * 2u, pb); }
;   DI void operator()(g8::Acc& acc, int pm, int pn, int wr, int wc, int fr, int fq) const {
;     ...
;     for (int ai = 0; ai < 2; ++ai)
; #pragma unroll
;       for (int m = 0; m < 4; ++m) {
;         const int row = pm * BM + ai * HALF + wr * 64 + m * 16 + fr; const float rs = rsqrtf(ssq[row] * (1.0f / DM) + RMS_EPS) * sc;
;         u32x4 wv[2];
; #pragma unroll
;         for (int bj = 0; bj < 2; ++bj) {
;           f32x4 o0 = acc[ai][bj][m][0] * rs, o1 = acc[ai][bj][m][1] * rs;
;           if (act) {
; #pragma unroll
;             for (int e = 0; e < 4; ++e) { const float a = fmaxf(o0[e], 0.f), b = fmaxf(o1[e], 0.f); o0[e] = a * a; o1[e] = b * b; } }
;           wv[bj] = pk8(o0, o1);
;         }
;         st_rows16(dst, (unsigned)ld * 2u, (unsigned)(row - fr), (unsigned)(pn * BM + wc * 64), fr, fq, wv[0], wv[1]);
;         __builtin_amdgcn_sched_barrier(0);
	v_cvt_pk_bf16_f32 v109, v110, v111
	v_cvt_pk_bf16_f32 v104, v104, v105
	v_cvt_pk_bf16_f32 v105, v106, v107
	v_mov_b32_dpp v113, v100 row_ror:8 row_mask:0xf bank_mask:0xf
	v_mov_b32_dpp v114, v101 row_ror:8 row_mask:0xf bank_mask:0xf
	v_mov_b32_dpp v115, v96 row_ror:8 row_mask:0xf bank_mask:0xf
	v_mov_b32_dpp v116, v97 row_ror:8 row_mask:0xf bank_mask:0xf
	v_cndmask_b32_e64 v96, v108, v113, s[4:5]
	v_cndmask_b32_e64 v97, v109, v114, s[4:5]
	v_cndmask_b32_e64 v98, v104, v115, s[4:5]
	v_cndmask_b32_e64 v99, v105, v116, s[4:5]
	v_cndmask_b32_e64 v100, v113, v108, s[4:5]
	v_cndmask_b32_e64 v101, v114, v109, s[4:5]
	v_cndmask_b32_e64 v102, v115, v104, s[4:5]
	v_cndmask_b32_e64 v103, v116, v105, s[4:5]
	global_store_dwordx4 v118, v[96:99], s[24:25] nt
	global_store_dwordx4 v117, v[100:103], s[24:25] nt
	s_or_b32 s1, s0, 32
	v_mov_b32_e32 v97, 0
	v_mov_b32_e32 v98, 0
	v_mov_b32_e32 v99, 0
	v_mov_b32_e32 v100, 0
	v_or_b32_e32 v101, s1, v142
	v_lshlrev_b32_e32 v101, 13, v101
	v_fmamk_f32 v96, v234, 0x3a800000, v149
	v_mul_f32_e32 v102, 0x4b800000, v96
	v_cmp_gt_f32_e32 vcc, s21, v96
	s_nop 1
	v_cndmask_b32_e32 v96, v96, v102, vcc
	v_rsq_f32_e32 v96, v96
	v_add_u32_e32 v102, v151, v101
	v_add3_u32 v101, v150, v101, s11
	v_mul_f32_e32 v103, 0x45800000, v96
	v_cndmask_b32_e32 v96, v96, v103, vcc
	v_pk_mul_f32 v[86:87], v[86:87], v[96:97] op_sel_hi:[1,0]
	v_pk_mul_f32 v[84:85], v[84:85], v[96:97] op_sel_hi:[1,0]
	v_pk_mul_f32 v[82:83], v[82:83], v[96:97] op_sel_hi:[1,0]
	v_pk_mul_f32 v[80:81], v[80:81], v[96:97] op_sel_hi:[1,0]
	v_pk_mul_f32 v[94:95], v[94:95], v[96:97] op_sel_hi:[1,0]
	v_pk_mul_f32 v[92:93], v[92:93], v[96:97] op_sel_hi:[1,0]
	v_pk_mul_f32 v[90:91], v[90:91], v[96:97] op_sel_hi:[1,0]
	v_pk_mul_f32 v[88:89], v[88:89], v[96:97] op_sel_hi:[1,0]
	v_max_f32_e32 v84, 0, v84
	v_max_f32_e32 v80, 0, v80
	v_max_f32_e32 v85, 0, v85
	v_max_f32_e32 v81, 0, v81
	v_max_f32_e32 v86, 0, v86
	v_max_f32_e32 v82, 0, v82
	v_max_f32_e32 v87, 0, v87
	v_max_f32_e32 v83, 0, v83
	v_max_f32_e32 v92, 0, v92
	v_max_f32_e32 v88, 0, v88
	v_max_f32_e32 v93, 0, v93
	v_max_f32_e32 v89, 0, v89
	v_max_f32_e32 v94, 0, v94
	v_max_f32_e32 v90, 0, v90
	v_max_f32_e32 v95, 0, v95
	v_max_f32_e32 v91, 0, v91
	v_pk_mul_f32 v[84:85], v[84:85], v[84:85]
	v_pk_mul_f32 v[80:81], v[80:81], v[80:81]
	v_pk_mul_f32 v[86:87], v[86:87], v[86:87]
	v_pk_mul_f32 v[82:83], v[82:83], v[82:83]
	v_pk_mul_f32 v[92:93], v[92:93], v[92:93]
	v_pk_mul_f32 v[88:89], v[88:89], v[88:89]
	v_pk_mul_f32 v[94:95], v[94:95], v[94:95]
	v_pk_mul_f32 v[90:91], v[90:91], v[90:91]
	v_cvt_pk_bf16_f32 v84, v84, v85
	v_cvt_pk_bf16_f32 v85, v86, v87
	v_cvt_pk_bf16_f32 v80, v80, v81
	v_cvt_pk_bf16_f32 v81, v82, v83
	v_cvt_pk_bf16_f32 v92, v92, v93
	v_cvt_pk_bf16_f32 v93, v94, v95
	v_cvt_pk_bf16_f32 v88, v88, v89
	v_cvt_pk_bf16_f32 v89, v90, v91
	v_mov_b32_dpp v97, v84 row_ror:8 row_mask:0xf bank_mask:0xf
	v_mov_b32_dpp v98, v85 row_ror:8 row_mask:0xf bank_mask:0xf
	v_mov_b32_dpp v99, v80 row_ror:8 row_mask:0xf bank_mask:0xf
	v_mov_b32_dpp v100, v81 row_ror:8 row_mask:0xf bank_mask:0xf
	v_cndmask_b32_e64 v80, v92, v97, s[4:5]
	v_cndmask_b32_e64 v81, v93, v98, s[4:5]
	v_cndmask_b32_e64 v82, v88, v99, s[4:5]
	v_cndmask_b32_e64 v83, v89, v100, s[4:5]
	v_cndmask_b32_e64 v84, v97, v92, s[4:5]
	v_cndmask_b32_e64 v85, v98, v93, s[4:5]
	v_cndmask_b32_e64 v86, v99, v88, s[4:5]
	v_cndmask_b32_e64 v87, v100, v89, s[4:5]
	global_store_dwordx4 v102, v[80:83], s[24:25] nt
	global_store_dwordx4 v101, v[84:87], s[24:25] nt
	s_or_b32 s1, s0, 48
	v_mov_b32_e32 v81, 0
	v_mov_b32_e32 v82, 0
	v_mov_b32_e32 v83, 0
	v_mov_b32_e32 v84, 0
	v_or_b32_e32 v85, s1, v142
	v_lshlrev_b32_e32 v85, 13, v85
	v_fmamk_f32 v80, v235, 0x3a800000, v149
	v_mul_f32_e32 v86, 0x4b800000, v80
	v_cmp_gt_f32_e32 vcc, s21, v80
	s_nop 1
	v_cndmask_b32_e32 v80, v80, v86, vcc
	v_rsq_f32_e32 v80, v80
	v_add_u32_e32 v86, v151, v85
	v_add3_u32 v85, v150, v85, s11
	v_mul_f32_e32 v87, 0x45800000, v80
	v_cndmask_b32_e32 v80, v80, v87, vcc
	v_pk_mul_f32 v[70:71], v[70:71], v[80:81] op_sel_hi:[1,0]
	v_pk_mul_f32 v[68:69], v[68:69], v[80:81] op_sel_hi:[1,0]
	v_pk_mul_f32 v[66:67], v[66:67], v[80:81] op_sel_hi:[1,0]
	v_pk_mul_f32 v[64:65], v[64:65], v[80:81] op_sel_hi:[1,0]
	v_pk_mul_f32 v[78:79], v[78:79], v[80:81] op_sel_hi:[1,0]
	v_pk_mul_f32 v[76:77], v[76:77], v[80:81] op_sel_hi:[1,0]
	v_pk_mul_f32 v[74:75], v[74:75], v[80:81] op_sel_hi:[1,0]
	v_pk_mul_f32 v[72:73], v[72:73], v[80:81] op_sel_hi:[1,0]
	v_max_f32_e32 v68, 0, v68
	v_max_f32_e32 v64, 0, v64
	v_max_f32_e32 v69, 0, v69
	v_max_f32_e32 v65, 0, v65
	v_max_f32_e32 v70, 0, v70
	v_max_f32_e32 v66, 0, v66
	v_max_f32_e32 v71, 0, v71
	v_max_f32_e32 v67, 0, v67
	v_max_f32_e32 v76, 0, v76
	v_max_f32_e32 v72, 0, v72
	v_max_f32_e32 v77, 0, v77
	v_max_f32_e32 v73, 0, v73
	v_max_f32_e32 v78, 0, v78
	v_max_f32_e32 v74, 0, v74
	v_max_f32_e32 v79, 0, v79
	v_max_f32_e32 v75, 0, v75
	v_pk_mul_f32 v[68:69], v[68:69], v[68:69]
	v_pk_mul_f32 v[64:65], v[64:65], v[64:65]
	v_pk_mul_f32 v[70:71], v[70:71], v[70:71]
	v_pk_mul_f32 v[66:67], v[66:67], v[66:67]
	v_pk_mul_f32 v[76:77], v[76:77], v[76:77]
	v_pk_mul_f32 v[72:73], v[72:73], v[72:73]
	v_pk_mul_f32 v[78:79], v[78:79], v[78:79]
	v_pk_mul_f32 v[74:75], v[74:75], v[74:75]
	v_cvt_pk_bf16_f32 v68, v68, v69
	v_cvt_pk_bf16_f32 v69, v70, v71
	v_cvt_pk_bf16_f32 v64, v64, v65
	v_cvt_pk_bf16_f32 v65, v66, v67
	v_cvt_pk_bf16_f32 v76, v76, v77
	v_cvt_pk_bf16_f32 v77, v78, v79
	v_cvt_pk_bf16_f32 v72, v72, v73
	v_cvt_pk_bf16_f32 v73, v74, v75
	v_mov_b32_dpp v81, v68 row_ror:8 row_mask:0xf bank_mask:0xf
	v_mov_b32_dpp v82, v69 row_ror:8 row_mask:0xf bank_mask:0xf
; DI u32x4 pk8(const f32x4& a, const f32x4& b) { u32x4 w; w.x = pk2(a[0], a[1]); w.y = pk2(a[2], a[3]); w.z = pk2(b[0], b[1]); w.w = pk2(b[2], b[3]); return w; }
; template <bool NT = false> DI void st_rows16(void* base, unsigned pitch_b, unsigned row0, unsigned col0, int fr, int fq, const u32x4& w0, const u32x4& w1) {
;   u32x4 x;
; #pragma unroll
;   for (int e = 0; e < 4; ++e) x[e] = (unsigned)__builtin_amdgcn_update_dpp(0, (int)w1[e], 0x128  , 0xf, 0xf, false);
;   const bool hi = fr >= 8;
;   u32x4 pa, pb;
; #pragma unroll
;   for (int e = 0; e < 4; ++e) { pa[e] = hi ? x[e] : w0[e]; pb[e] = hi ? w0[e] : x[e]; }
;   const unsigned ra = row0 + (unsigned)(fr & 7), ca = col0 + 8u * fq + (hi ? 32u : 0u), cb = col0 + 8u * fq + (hi ? 0u : 32u);
;   if (NT) { __builtin_nontemporal_store(pa, (u32x4*)((char*)base + (ra * pitch_b + ca * 2u))); __builtin_nontemporal_store(pb, (u32x4*)((char*)base + ((ra + 8u) * pitch_b + cb * 2u))); }
;   else { gst<u32x4>(base, ra * pitch_b + ca * 2u, pa); gst<u32x4>(base, (ra + 8u) * pitch_b + cb * 2u, pb); }
;   DI void operator()(g8::Acc& acc, int pm, int pn, int wr, int wc, int fr, int fq) const {
;     ...
;     for (int ai = 0; ai < 2; ++ai)
; #pragma unroll
;       for (int m = 0; m < 4; ++m) {
;         const int row = pm * BM + ai * HALF + wr * 64 + m * 16 + fr; const float rs = rsqrtf(ssq[row] * (1.0f / DM) + RMS_EPS) * sc;
;         u32x4 wv[2];
; #pragma unroll
;         for (int bj = 0; bj < 2; ++bj) {
;           f32x4 o0 = acc[ai][bj][m][0] * rs, o1 = acc[ai][bj][m][1] * rs;
;           if (act) {
; #pragma unroll
;             for (int e = 0; e < 4; ++e) { const float a = fmaxf(o0[e], 0.f), b = fmaxf(o1[e], 0.f); o0[e] = a * a; o1[e] = b * b; } }
;           wv[bj] = pk8(o0, o1);
;         }
;         st_rows16(dst, (unsigned)ld * 2u, (unsigned)(row - fr), (unsigned)(pn * BM + wc * 64), fr, fq, wv[0], wv[1]);
;         __builtin_amdgcn_sched_barrier(0);
	v_mov_b32_dpp v83, v64 row_ror:8 row_mask:0xf bank_mask:0xf
	v_mov_b32_dpp v84, v65 row_ror:8 row_mask:0xf bank_mask:0xf
	v_cndmask_b32_e64 v64, v76, v81, s[4:5]
	v_cndmask_b32_e64 v65, v77, v82, s[4:5]
	v_cndmask_b32_e64 v66, v72, v83, s[4:5]
	v_cndmask_b32_e64 v67, v73, v84, s[4:5]
	v_cndmask_b32_e64 v68, v81, v76, s[4:5]
	v_cndmask_b32_e64 v69, v82, v77, s[4:5]
	v_cndmask_b32_e64 v70, v83, v72, s[4:5]
	v_cndmask_b32_e64 v71, v84, v73, s[4:5]
	global_store_dwordx4 v86, v[64:67], s[24:25] nt
	global_store_dwordx4 v85, v[68:71], s[24:25] nt
	s_add_i32 s1, s0, 0x80
	v_mov_b32_e32 v65, 0
	v_mov_b32_e32 v66, 0
	v_mov_b32_e32 v67, 0
	v_mov_b32_e32 v68, 0
	v_or_b32_e32 v69, s1, v142
	v_lshlrev_b32_e32 v69, 13, v69
	v_fmamk_f32 v64, v236, 0x3a800000, v149
	v_mul_f32_e32 v70, 0x4b800000, v64
	v_cmp_gt_f32_e32 vcc, s21, v64
	s_nop 1
	v_cndmask_b32_e32 v64, v64, v70, vcc
	v_rsq_f32_e32 v64, v64
	v_add_u32_e32 v70, v151, v69
	v_add3_u32 v69, v150, v69, s11
	v_mul_f32_e32 v71, 0x45800000, v64
	v_cndmask_b32_e32 v64, v64, v71, vcc
	v_pk_mul_f32 v[54:55], v[54:55], v[64:65] op_sel_hi:[1,0]
	v_pk_mul_f32 v[52:53], v[52:53], v[64:65] op_sel_hi:[1,0]
	v_pk_mul_f32 v[50:51], v[50:51], v[64:65] op_sel_hi:[1,0]
	v_pk_mul_f32 v[48:49], v[48:49], v[64:65] op_sel_hi:[1,0]
	v_pk_mul_f32 v[62:63], v[62:63], v[64:65] op_sel_hi:[1,0]
	v_pk_mul_f32 v[60:61], v[60:61], v[64:65] op_sel_hi:[1,0]
	v_pk_mul_f32 v[58:59], v[58:59], v[64:65] op_sel_hi:[1,0]
	v_pk_mul_f32 v[56:57], v[56:57], v[64:65] op_sel_hi:[1,0]
	v_max_f32_e32 v52, 0, v52
	v_max_f32_e32 v48, 0, v48
	v_max_f32_e32 v53, 0, v53
	v_max_f32_e32 v49, 0, v49
	v_max_f32_e32 v54, 0, v54
	v_max_f32_e32 v50, 0, v50
	v_max_f32_e32 v55, 0, v55
	v_max_f32_e32 v51, 0, v51
	v_max_f32_e32 v60, 0, v60
	v_max_f32_e32 v56, 0, v56
	v_max_f32_e32 v61, 0, v61
	v_max_f32_e32 v57, 0, v57
	v_max_f32_e32 v62, 0, v62
	v_max_f32_e32 v58, 0, v58
	v_max_f32_e32 v63, 0, v63
	v_max_f32_e32 v59, 0, v59
	v_pk_mul_f32 v[52:53], v[52:53], v[52:53]
	v_pk_mul_f32 v[48:49], v[48:49], v[48:49]
	v_pk_mul_f32 v[54:55], v[54:55], v[54:55]
	v_pk_mul_f32 v[50:51], v[50:51], v[50:51]
	v_pk_mul_f32 v[60:61], v[60:61], v[60:61]
	v_pk_mul_f32 v[56:57], v[56:57], v[56:57]
	v_pk_mul_f32 v[62:63], v[62:63], v[62:63]
	v_pk_mul_f32 v[58:59], v[58:59], v[58:59]
	v_cvt_pk_bf16_f32 v52, v52, v53
	v_cvt_pk_bf16_f32 v53, v54, v55
	v_cvt_pk_bf16_f32 v48, v48, v49
	v_cvt_pk_bf16_f32 v49, v50, v51
	v_cvt_pk_bf16_f32 v60, v60, v61
	v_cvt_pk_bf16_f32 v61, v62, v63
	v_cvt_pk_bf16_f32 v56, v56, v57
	v_cvt_pk_bf16_f32 v57, v58, v59
	v_mov_b32_dpp v65, v52 row_ror:8 row_mask:0xf bank_mask:0xf
	v_mov_b32_dpp v66, v53 row_ror:8 row_mask:0xf bank_mask:0xf
	v_mov_b32_dpp v67, v48 row_ror:8 row_mask:0xf bank_mask:0xf
	v_mov_b32_dpp v68, v49 row_ror:8 row_mask:0xf bank_mask:0xf
	v_cndmask_b32_e64 v48, v60, v65, s[4:5]
	v_cndmask_b32_e64 v49, v61, v66, s[4:5]
	v_cndmask_b32_e64 v50, v56, v67, s[4:5]
	v_cndmask_b32_e64 v51, v57, v68, s[4:5]
	v_cndmask_b32_e64 v52, v65, v60, s[4:5]
	v_cndmask_b32_e64 v53, v66, v61, s[4:5]
	v_cndmask_b32_e64 v54, v67, v56, s[4:5]
	v_cndmask_b32_e64 v55, v68, v57, s[4:5]
	global_store_dwordx4 v70, v[48:51], s[24:25] nt
	global_store_dwordx4 v69, v[52:55], s[24:25] nt
	s_add_i32 s1, s0, 0x90
	v_mov_b32_e32 v49, 0
	v_mov_b32_e32 v50, 0
	v_mov_b32_e32 v51, 0
	v_mov_b32_e32 v52, 0
	v_or_b32_e32 v53, s1, v142
	v_lshlrev_b32_e32 v53, 13, v53
	v_fmamk_f32 v48, v237, 0x3a800000, v149
	v_mul_f32_e32 v54, 0x4b800000, v48
	v_cmp_gt_f32_e32 vcc, s21, v48
	s_nop 1
	v_cndmask_b32_e32 v48, v48, v54, vcc
	v_rsq_f32_e32 v48, v48
	v_add_u32_e32 v54, v151, v53
	v_add3_u32 v53, v150, v53, s11
	v_mul_f32_e32 v55, 0x45800000, v48
	v_cndmask_b32_e32 v48, v48, v55, vcc
	v_pk_mul_f32 v[38:39], v[38:39], v[48:49] op_sel_hi:[1,0]
	v_pk_mul_f32 v[36:37], v[36:37], v[48:49] op_sel_hi:[1,0]
	v_pk_mul_f32 v[34:35], v[34:35], v[48:49] op_sel_hi:[1,0]
	v_pk_mul_f32 v[32:33], v[32:33], v[48:49] op_sel_hi:[1,0]
	v_pk_mul_f32 v[46:47], v[46:47], v[48:49] op_sel_hi:[1,0]
	v_pk_mul_f32 v[44:45], v[44:45], v[48:49] op_sel_hi:[1,0]
	v_pk_mul_f32 v[42:43], v[42:43], v[48:49] op_sel_hi:[1,0]
	v_pk_mul_f32 v[40:41], v[40:41], v[48:49] op_sel_hi:[1,0]
	v_max_f32_e32 v36, 0, v36
	v_max_f32_e32 v32, 0, v32
	v_max_f32_e32 v37, 0, v37
	v_max_f32_e32 v33, 0, v33
	v_max_f32_e32 v38, 0, v38
	v_max_f32_e32 v34, 0, v34
	v_max_f32_e32 v39, 0, v39
	v_max_f32_e32 v35, 0, v35
	v_max_f32_e32 v44, 0, v44
	v_max_f32_e32 v40, 0, v40
	v_max_f32_e32 v45, 0, v45
	v_max_f32_e32 v41, 0, v41
	v_max_f32_e32 v46, 0, v46
	v_max_f32_e32 v42, 0, v42
	v_max_f32_e32 v47, 0, v47
	v_max_f32_e32 v43, 0, v43
	v_pk_mul_f32 v[36:37], v[36:37], v[36:37]
	v_pk_mul_f32 v[32:33], v[32:33], v[32:33]
	v_pk_mul_f32 v[38:39], v[38:39], v[38:39]
	v_pk_mul_f32 v[34:35], v[34:35], v[34:35]
	v_pk_mul_f32 v[44:45], v[44:45], v[44:45]
	v_pk_mul_f32 v[40:41], v[40:41], v[40:41]
	v_pk_mul_f32 v[46:47], v[46:47], v[46:47]
	v_pk_mul_f32 v[42:43], v[42:43], v[42:43]
	v_cvt_pk_bf16_f32 v36, v36, v37
	v_cvt_pk_bf16_f32 v37, v38, v39
	v_cvt_pk_bf16_f32 v32, v32, v33
	v_cvt_pk_bf16_f32 v33, v34, v35
	v_cvt_pk_bf16_f32 v44, v44, v45
	v_cvt_pk_bf16_f32 v45, v46, v47
	v_cvt_pk_bf16_f32 v40, v40, v41
	v_cvt_pk_bf16_f32 v41, v42, v43
	v_mov_b32_dpp v49, v36 row_ror:8 row_mask:0xf bank_mask:0xf
	v_mov_b32_dpp v50, v37 row_ror:8 row_mask:0xf bank_mask:0xf
	v_mov_b32_dpp v51, v32 row_ror:8 row_mask:0xf bank_mask:0xf
	v_mov_b32_dpp v52, v33 row_ror:8 row_mask:0xf bank_mask:0xf
	v_cndmask_b32_e64 v32, v44, v49, s[4:5]
	v_cndmask_b32_e64 v33, v45, v50, s[4:5]
	v_cndmask_b32_e64 v34, v40, v51, s[4:5]
	v_cndmask_b32_e64 v35, v41, v52, s[4:5]
; DI u32x4 pk8(const f32x4& a, const f32x4& b) { u32x4 w; w.x = pk2(a[0], a[1]); w.y = pk2(a[2], a[3]); w.z = pk2(b[0], b[1]); w.w = pk2(b[2], b[3]); return w; }
; template <bool NT = false> DI void st_rows16(void* base, unsigned pitch_b, unsigned row0, unsigned col0, int fr, int fq, const u32x4& w0, const u32x4& w1) {
;   u32x4 x;
; #pragma unroll
;   for (int e = 0; e < 4; ++e) x[e] = (unsigned)__builtin_amdgcn_update_dpp(0, (int)w1[e], 0x128  , 0xf, 0xf, false);
;   const bool hi = fr >= 8;
;   u32x4 pa, pb;
; #pragma unroll
;   for (int e = 0; e < 4; ++e) { pa[e] = hi ? x[e] : w0[e]; pb[e] = hi ? w0[e] : x[e]; }
;   const unsigned ra = row0 + (unsigned)(fr & 7), ca = col0 + 8u * fq + (hi ? 32u : 0u), cb = col0 + 8u * fq + (hi ? 0u : 32u);
;   if (NT) { __builtin_nontemporal_store(pa, (u32x4*)((char*)base + (ra * pitch_b + ca * 2u))); __builtin_nontemporal_store(pb, (u32x4*)((char*)base + ((ra + 8u) * pitch_b + cb * 2u))); }
;   else { gst<u32x4>(base, ra * pitch_b + ca * 2u, pa); gst<u32x4>(base, (ra + 8u) * pitch_b + cb * 2u, pb); }
;   DI void operator()(g8::Acc& acc, int pm, int pn, int wr, int wc, int fr, int fq) const {
;     ...
;     for (int ai = 0; ai < 2; ++ai)
; #pragma unroll
;       for (int m = 0; m < 4; ++m) {
;         const int row = pm * BM + ai * HALF + wr * 64 + m * 16 + fr; const float rs = rsqrtf(ssq[row] * (1.0f / DM) + RMS_EPS) * sc;
;         u32x4 wv[2];
; #pragma unroll
;         for (int bj = 0; bj < 2; ++bj) {
;           f32x4 o0 = acc[ai][bj][m][0] * rs, o1 = acc[ai][bj][m][1] * rs;
;           if (act) {
; #pragma unroll
;             for (int e = 0; e < 4; ++e) { const float a = fmaxf(o0[e], 0.f), b = fmaxf(o1[e], 0.f); o0[e] = a * a; o1[e] = b * b; } }
;           wv[bj] = pk8(o0, o1);
;         }
;         st_rows16(dst, (unsigned)ld * 2u, (unsigned)(row - fr), (unsigned)(pn * BM + wc * 64), fr, fq, wv[0], wv[1]);
;         __builtin_amdgcn_sched_barrier(0);
	v_cndmask_b32_e64 v36, v49, v44, s[4:5]
	v_cndmask_b32_e64 v37, v50, v45, s[4:5]
	v_cndmask_b32_e64 v38, v51, v40, s[4:5]
	v_cndmask_b32_e64 v39, v52, v41, s[4:5]
	global_store_dwordx4 v54, v[32:35], s[24:25] nt
	global_store_dwordx4 v53, v[36:39], s[24:25] nt
	s_add_i32 s1, s0, 0xa0
	v_mov_b32_e32 v33, 0
	v_mov_b32_e32 v34, 0
	v_mov_b32_e32 v35, 0
	v_mov_b32_e32 v36, 0
	v_or_b32_e32 v37, s1, v142
	v_lshlrev_b32_e32 v37, 13, v37
	v_fmamk_f32 v32, v238, 0x3a800000, v149
	v_mul_f32_e32 v38, 0x4b800000, v32
	v_cmp_gt_f32_e32 vcc, s21, v32
	s_nop 1
	v_cndmask_b32_e32 v32, v32, v38, vcc
	v_rsq_f32_e32 v32, v32
	v_add_u32_e32 v38, v151, v37
	v_add3_u32 v37, v150, v37, s11
	v_mul_f32_e32 v39, 0x45800000, v32
	v_cndmask_b32_e32 v32, v32, v39, vcc
	v_pk_mul_f32 v[22:23], v[22:23], v[32:33] op_sel_hi:[1,0]
	v_pk_mul_f32 v[20:21], v[20:21], v[32:33] op_sel_hi:[1,0]
	v_pk_mul_f32 v[18:19], v[18:19], v[32:33] op_sel_hi:[1,0]
	v_pk_mul_f32 v[16:17], v[16:17], v[32:33] op_sel_hi:[1,0]
	v_pk_mul_f32 v[30:31], v[30:31], v[32:33] op_sel_hi:[1,0]
	v_pk_mul_f32 v[28:29], v[28:29], v[32:33] op_sel_hi:[1,0]
	v_pk_mul_f32 v[26:27], v[26:27], v[32:33] op_sel_hi:[1,0]
	v_pk_mul_f32 v[24:25], v[24:25], v[32:33] op_sel_hi:[1,0]
	v_max_f32_e32 v20, 0, v20
	v_max_f32_e32 v16, 0, v16
	v_max_f32_e32 v21, 0, v21
	v_max_f32_e32 v17, 0, v17
	v_max_f32_e32 v22, 0, v22
	v_max_f32_e32 v18, 0, v18
	v_max_f32_e32 v23, 0, v23
	v_max_f32_e32 v19, 0, v19
	v_max_f32_e32 v28, 0, v28
	v_max_f32_e32 v24, 0, v24
	v_max_f32_e32 v29, 0, v29
	v_max_f32_e32 v25, 0, v25
	v_max_f32_e32 v30, 0, v30
	v_max_f32_e32 v26, 0, v26
	v_max_f32_e32 v31, 0, v31
	v_max_f32_e32 v27, 0, v27
	v_pk_mul_f32 v[20:21], v[20:21], v[20:21]
	v_pk_mul_f32 v[16:17], v[16:17], v[16:17]
	v_pk_mul_f32 v[22:23], v[22:23], v[22:23]
	v_pk_mul_f32 v[18:19], v[18:19], v[18:19]
	v_pk_mul_f32 v[28:29], v[28:29], v[28:29]
	v_pk_mul_f32 v[24:25], v[24:25], v[24:25]
	v_pk_mul_f32 v[30:31], v[30:31], v[30:31]
	v_pk_mul_f32 v[26:27], v[26:27], v[26:27]
	v_cvt_pk_bf16_f32 v20, v20, v21
	v_cvt_pk_bf16_f32 v21, v22, v23
	v_cvt_pk_bf16_f32 v16, v16, v17
	v_cvt_pk_bf16_f32 v17, v18, v19
	v_cvt_pk_bf16_f32 v28, v28, v29
	v_cvt_pk_bf16_f32 v29, v30, v31
	v_cvt_pk_bf16_f32 v24, v24, v25
	v_cvt_pk_bf16_f32 v25, v26, v27
	v_mov_b32_dpp v33, v20 row_ror:8 row_mask:0xf bank_mask:0xf
	v_mov_b32_dpp v34, v21 row_ror:8 row_mask:0xf bank_mask:0xf
	v_mov_b32_dpp v35, v16 row_ror:8 row_mask:0xf bank_mask:0xf
	v_mov_b32_dpp v36, v17 row_ror:8 row_mask:0xf bank_mask:0xf
	v_cndmask_b32_e64 v16, v28, v33, s[4:5]
	v_cndmask_b32_e64 v17, v29, v34, s[4:5]
	v_cndmask_b32_e64 v18, v24, v35, s[4:5]
	v_cndmask_b32_e64 v19, v25, v36, s[4:5]
	v_cndmask_b32_e64 v20, v33, v28, s[4:5]
	v_cndmask_b32_e64 v21, v34, v29, s[4:5]
	v_cndmask_b32_e64 v22, v35, v24, s[4:5]
	v_cndmask_b32_e64 v23, v36, v25, s[4:5]
	global_store_dwordx4 v38, v[16:19], s[24:25] nt
	global_store_dwordx4 v37, v[20:23], s[24:25] nt
	s_addk_i32 s0, 0xb0
	v_mov_b32_e32 v17, 0
	v_mov_b32_e32 v18, 0
	v_mov_b32_e32 v19, 0
	v_mov_b32_e32 v20, 0
	v_or_b32_e32 v21, s0, v142
	v_lshlrev_b32_e32 v21, 13, v21
	v_fmamk_f32 v16, v239, 0x3a800000, v149
	v_mul_f32_e32 v22, 0x4b800000, v16
	v_cmp_gt_f32_e32 vcc, s21, v16
	s_nop 1
	v_cndmask_b32_e32 v16, v16, v22, vcc
	v_rsq_f32_e32 v16, v16
	v_add_u32_e32 v22, v151, v21
	v_add3_u32 v21, v150, v21, s11
	v_mul_f32_e32 v23, 0x45800000, v16
	v_cndmask_b32_e32 v16, v16, v23, vcc
	v_pk_mul_f32 v[6:7], v[6:7], v[16:17] op_sel_hi:[1,0]
	v_pk_mul_f32 v[4:5], v[4:5], v[16:17] op_sel_hi:[1,0]
	v_pk_mul_f32 v[2:3], v[2:3], v[16:17] op_sel_hi:[1,0]
	v_pk_mul_f32 v[0:1], v[0:1], v[16:17] op_sel_hi:[1,0]
	v_pk_mul_f32 v[14:15], v[14:15], v[16:17] op_sel_hi:[1,0]
	v_pk_mul_f32 v[12:13], v[12:13], v[16:17] op_sel_hi:[1,0]
	v_pk_mul_f32 v[10:11], v[10:11], v[16:17] op_sel_hi:[1,0]
	v_pk_mul_f32 v[8:9], v[8:9], v[16:17] op_sel_hi:[1,0]
	v_max_f32_e32 v4, 0, v4
	v_max_f32_e32 v0, 0, v0
	v_max_f32_e32 v5, 0, v5
	v_max_f32_e32 v1, 0, v1
	v_max_f32_e32 v6, 0, v6
	v_max_f32_e32 v2, 0, v2
	v_max_f32_e32 v7, 0, v7
	v_max_f32_e32 v3, 0, v3
	v_max_f32_e32 v12, 0, v12
	v_max_f32_e32 v8, 0, v8
	v_max_f32_e32 v13, 0, v13
	v_max_f32_e32 v9, 0, v9
	v_max_f32_e32 v14, 0, v14
	v_max_f32_e32 v10, 0, v10
	v_max_f32_e32 v15, 0, v15
	v_max_f32_e32 v11, 0, v11
	v_pk_mul_f32 v[4:5], v[4:5], v[4:5]
	v_pk_mul_f32 v[0:1], v[0:1], v[0:1]
	v_pk_mul_f32 v[6:7], v[6:7], v[6:7]
	v_pk_mul_f32 v[2:3], v[2:3], v[2:3]
	v_pk_mul_f32 v[12:13], v[12:13], v[12:13]
	v_pk_mul_f32 v[8:9], v[8:9], v[8:9]
	v_pk_mul_f32 v[14:15], v[14:15], v[14:15]
	v_pk_mul_f32 v[10:11], v[10:11], v[10:11]
	v_cvt_pk_bf16_f32 v4, v4, v5
	v_cvt_pk_bf16_f32 v5, v6, v7
	v_cvt_pk_bf16_f32 v0, v0, v1
	v_cvt_pk_bf16_f32 v1, v2, v3
	v_cvt_pk_bf16_f32 v10, v10, v11
	v_cvt_pk_bf16_f32 v8, v8, v9
	v_cvt_pk_bf16_f32 v9, v14, v15
	v_cvt_pk_bf16_f32 v11, v12, v13
	v_mov_b32_dpp v17, v4 row_ror:8 row_mask:0xf bank_mask:0xf
	v_mov_b32_dpp v18, v5 row_ror:8 row_mask:0xf bank_mask:0xf
	v_mov_b32_dpp v19, v0 row_ror:8 row_mask:0xf bank_mask:0xf
	v_mov_b32_dpp v20, v1 row_ror:8 row_mask:0xf bank_mask:0xf
	v_cndmask_b32_e64 v0, v11, v17, s[4:5]
	v_cndmask_b32_e64 v1, v9, v18, s[4:5]
	v_cndmask_b32_e64 v2, v8, v19, s[4:5]
	v_cndmask_b32_e64 v3, v10, v20, s[4:5]
	v_cndmask_b32_e64 v4, v17, v11, s[4:5]
	v_cndmask_b32_e64 v5, v18, v9, s[4:5]
	v_cndmask_b32_e64 v6, v19, v8, s[4:5]
	v_cndmask_b32_e64 v7, v20, v10, s[4:5]
	global_store_dwordx4 v22, v[0:3], s[24:25] nt
	global_store_dwordx4 v21, v[4:7], s[24:25] nt
	s_andn2_b64 vcc, exec, s[36:37]
	s_mov_b64 s[0:1], -1
	s_cbranch_vccnz .LBB0_756
	s_andn2_b64 vcc, exec, s[6:7]
	s_cbranch_vccnz .LBB0_755
	s_barrier
	s_branch .LBB0_755
